# instruction selection: GEMM accumulator clears use v_mov_b64 (64 instead of 127 moves per unit)
# speedup vs baseline: 1.0018x; 1.0018x over previous
; template <class Epi, class Sched, bool ALIGN_EPI = false, bool SP2 = false, bool TILED_A = false, bool TILED_B = false, bool I8 = false>
; __device__ __forceinline__ void gemm_phase(PG8_LAS unsigned char* lds, const Gemm g, const Sched& S, const Epi& E) {
;     ...
;     for (;;) {
;         const bool has_next = S.next(ui + 1, nxt);
;         const char* nA = has_next ? (const char*)g.A + (size_t)nxt.pm * tstep : cA; const char* nB = has_next ? (const char*)g.Bt + (size_t)nxt.pn * tstep : cB;
;     ...
; #pragma unroll
;         for (int a = 0; a < 2; ++a)
; #pragma unroll
;             for (int b = 0; b < 2; ++b)
; #pragma unroll
;                 for (int m = 0; m < 4; ++m)
; #pragma unroll
;                     for (int n = 0; n < 2; ++n) acc[a][b][m][n] = MT<I8>::zero();
.LBB0_200:
	s_ashr_i32 s43, s42, 31
	s_lshl_b64 s[44:45], s[42:43], 21
	s_add_u32 s44, s2, s44
	s_addc_u32 s45, s3, s45
	s_and_b64 s[46:47], s[40:41], exec
	s_cselect_b32 s43, s45, s55
	s_cselect_b32 s60, s44, s54
	s_ashr_i32 s37, s36, 31
	s_lshl_b64 s[46:47], s[36:37], 21
	s_add_u32 s46, s20, s46
	s_addc_u32 s47, s25, s47
	s_and_b64 s[56:57], s[40:41], exec
	s_cselect_b32 s37, s47, s13
	s_cselect_b32 s61, s46, s12
	s_add_u32 s62, s12, 0x10000
	s_addc_u32 s63, s13, 0
	s_add_u32 s54, s54, 0x100080
	v_mov_b32_e32 v2, 0
	s_addc_u32 s55, s55, 0
	s_mov_b32 s66, -2
	v_mov_b32_e32 v3, v2
	v_mov_b64_e32 v[4:5], 0
	v_mov_b64_e32 v[6:7], 0
	v_mov_b64_e32 v[8:9], 0
	v_mov_b64_e32 v[18:19], 0
	v_mov_b64_e32 v[20:21], 0
	v_mov_b64_e32 v[22:23], 0
	v_mov_b64_e32 v[24:25], 0
	v_mov_b64_e32 v[34:35], 0
	v_mov_b64_e32 v[36:37], 0
	v_mov_b64_e32 v[38:39], 0
	v_mov_b64_e32 v[40:41], 0
	v_mov_b64_e32 v[50:51], 0
	v_mov_b64_e32 v[52:53], 0
	v_mov_b64_e32 v[54:55], 0
	v_mov_b64_e32 v[56:57], 0
	v_mov_b64_e32 v[10:11], 0
	v_mov_b64_e32 v[12:13], 0
	v_mov_b64_e32 v[14:15], 0
	v_mov_b64_e32 v[16:17], 0
	v_mov_b64_e32 v[26:27], 0
	v_mov_b64_e32 v[28:29], 0
	v_mov_b64_e32 v[30:31], 0
	v_mov_b64_e32 v[32:33], 0
	v_mov_b64_e32 v[42:43], 0
	v_mov_b64_e32 v[44:45], 0
	v_mov_b64_e32 v[46:47], 0
	v_mov_b64_e32 v[48:49], 0
	v_mov_b64_e32 v[58:59], 0
	v_mov_b64_e32 v[60:61], 0
	v_mov_b64_e32 v[62:63], 0
	v_mov_b64_e32 v[64:65], 0
	v_mov_b64_e32 v[66:67], 0
	v_mov_b64_e32 v[68:69], 0
	v_mov_b64_e32 v[70:71], 0
	v_mov_b64_e32 v[72:73], 0
	v_mov_b64_e32 v[82:83], 0
	v_mov_b64_e32 v[84:85], 0
	v_mov_b64_e32 v[86:87], 0
	v_mov_b64_e32 v[88:89], 0
	v_mov_b64_e32 v[98:99], 0
	v_mov_b64_e32 v[100:101], 0
	v_mov_b64_e32 v[102:103], 0
	v_mov_b64_e32 v[104:105], 0
	v_mov_b64_e32 v[116:117], 0
	v_mov_b64_e32 v[118:119], 0
	v_mov_b64_e32 v[120:121], 0
	v_mov_b64_e32 v[122:123], 0
	v_mov_b64_e32 v[74:75], 0
	v_mov_b64_e32 v[76:77], 0
	v_mov_b64_e32 v[78:79], 0
	v_mov_b64_e32 v[80:81], 0
	v_mov_b64_e32 v[90:91], 0
	v_mov_b64_e32 v[92:93], 0
	v_mov_b64_e32 v[94:95], 0
	v_mov_b64_e32 v[96:97], 0
	v_mov_b64_e32 v[106:107], 0
	v_mov_b64_e32 v[108:109], 0
	v_mov_b64_e32 v[110:111], 0
	v_mov_b64_e32 v[112:113], 0
	v_mov_b64_e32 v[124:125], 0
	v_mov_b64_e32 v[126:127], 0
	v_mov_b64_e32 v[128:129], 0
	v_mov_b64_e32 v[130:131], 0

; template <class Epi, class Sched, bool ALIGN_EPI = false, bool SP2 = false, bool TILED_A = false, bool TILED_B = false, bool I8 = false>
; __device__ __forceinline__ void gemm_phase(PG8_LAS unsigned char* lds, const Gemm g, const Sched& S, const Epi& E) {
;     ...
;     for (;;) {
;         const bool has_next = S.next(ui + 1, nxt);
;         const char* nA = has_next ? (const char*)g.A + (size_t)nxt.pm * tstep : cA; const char* nB = has_next ? (const char*)g.Bt + (size_t)nxt.pn * tstep : cB;
;     ...
; #pragma unroll
;         for (int a = 0; a < 2; ++a)
; #pragma unroll
;             for (int b = 0; b < 2; ++b)
; #pragma unroll
;                 for (int m = 0; m < 4; ++m)
; #pragma unroll
;                     for (int n = 0; n < 2; ++n) acc[a][b][m][n] = MT<I8>::zero();
.LBB0_218:
	s_ashr_i32 s57, s56, 31
	s_lshl_b64 s[12:13], s[56:57], 20
	s_add_u32 s58, s34, s12
	s_addc_u32 s59, s35, s13
	s_and_b64 s[12:13], s[40:41], exec
	s_cselect_b32 s3, s59, s11
	s_cselect_b32 s7, s58, s10
	s_ashr_i32 s55, s54, 31
	s_lshl_b64 s[12:13], s[54:55], 20
	s_add_u32 s60, s36, s12
	s_addc_u32 s61, s37, s13
	s_and_b64 s[12:13], s[40:41], exec
	s_cselect_b32 s20, s61, s9
	s_cselect_b32 s22, s60, s8
	s_add_u32 s23, s8, 0x10000
	s_addc_u32 s24, s9, 0
	s_add_u32 s8, s10, 0x80080
	v_mov_b32_e32 v2, 0
	s_addc_u32 s9, s11, 0
	s_mov_b32 s25, -2
	v_mov_b32_e32 v3, v2
	v_mov_b64_e32 v[4:5], 0
	v_mov_b64_e32 v[6:7], 0
	v_mov_b64_e32 v[8:9], 0
	v_mov_b64_e32 v[18:19], 0
	v_mov_b64_e32 v[20:21], 0
	v_mov_b64_e32 v[22:23], 0
	v_mov_b64_e32 v[24:25], 0
	v_mov_b64_e32 v[34:35], 0
	v_mov_b64_e32 v[36:37], 0
	v_mov_b64_e32 v[38:39], 0
	v_mov_b64_e32 v[40:41], 0
	v_mov_b64_e32 v[50:51], 0
	v_mov_b64_e32 v[52:53], 0
	v_mov_b64_e32 v[54:55], 0
	v_mov_b64_e32 v[56:57], 0
	v_mov_b64_e32 v[10:11], 0
	v_mov_b64_e32 v[12:13], 0
	v_mov_b64_e32 v[14:15], 0
	v_mov_b64_e32 v[16:17], 0
	v_mov_b64_e32 v[26:27], 0
	v_mov_b64_e32 v[28:29], 0
	v_mov_b64_e32 v[30:31], 0
	v_mov_b64_e32 v[32:33], 0
	v_mov_b64_e32 v[42:43], 0
	v_mov_b64_e32 v[44:45], 0
	v_mov_b64_e32 v[46:47], 0
	v_mov_b64_e32 v[48:49], 0
	v_mov_b64_e32 v[58:59], 0
	v_mov_b64_e32 v[60:61], 0
	v_mov_b64_e32 v[62:63], 0
	v_mov_b64_e32 v[64:65], 0
	v_mov_b64_e32 v[66:67], 0
	v_mov_b64_e32 v[68:69], 0
	v_mov_b64_e32 v[70:71], 0
	v_mov_b64_e32 v[72:73], 0
	v_mov_b64_e32 v[82:83], 0
	v_mov_b64_e32 v[84:85], 0
	v_mov_b64_e32 v[86:87], 0
	v_mov_b64_e32 v[88:89], 0
	v_mov_b64_e32 v[98:99], 0
	v_mov_b64_e32 v[100:101], 0
	v_mov_b64_e32 v[102:103], 0
	v_mov_b64_e32 v[104:105], 0
	v_mov_b64_e32 v[116:117], 0
	v_mov_b64_e32 v[118:119], 0
	v_mov_b64_e32 v[120:121], 0
	v_mov_b64_e32 v[122:123], 0
	v_mov_b64_e32 v[74:75], 0
	v_mov_b64_e32 v[76:77], 0
	v_mov_b64_e32 v[78:79], 0
	v_mov_b64_e32 v[80:81], 0
	v_mov_b64_e32 v[90:91], 0
	v_mov_b64_e32 v[92:93], 0
	v_mov_b64_e32 v[94:95], 0
	v_mov_b64_e32 v[96:97], 0
	v_mov_b64_e32 v[106:107], 0
	v_mov_b64_e32 v[108:109], 0
	v_mov_b64_e32 v[110:111], 0
	v_mov_b64_e32 v[112:113], 0
	v_mov_b64_e32 v[124:125], 0
	v_mov_b64_e32 v[126:127], 0
	v_mov_b64_e32 v[128:129], 0
	v_mov_b64_e32 v[130:131], 0

; template <class Epi, class Sched, bool ALIGN_EPI = false, bool SP2 = false, bool TILED_A = false, bool TILED_B = false, bool I8 = false>
; __device__ __forceinline__ void gemm_phase(PG8_LAS unsigned char* lds, const Gemm g, const Sched& S, const Epi& E) {
;     ...
;     for (;;) {
;         const bool has_next = S.next(ui + 1, nxt);
;         const char* nA = has_next ? (const char*)g.A + (size_t)nxt.pm * tstep : cA; const char* nB = has_next ? (const char*)g.Bt + (size_t)nxt.pn * tstep : cB;
;     ...
; #pragma unroll
;         for (int a = 0; a < 2; ++a)
; #pragma unroll
;             for (int b = 0; b < 2; ++b)
; #pragma unroll
;                 for (int m = 0; m < 4; ++m)
; #pragma unroll
;                     for (int n = 0; n < 2; ++n) acc[a][b][m][n] = MT<I8>::zero();
.LBB0_566:
	s_ashr_i32 s37, s36, 31
	s_lshl_b64 s[16:17], s[36:37], 21
	s_add_u32 s38, s2, s16
	s_addc_u32 s39, s3, s17
	s_and_b64 s[16:17], s[40:41], exec
	s_cselect_b32 s37, s39, s45
	s_cselect_b32 s52, s38, s44
	s_ashr_i32 s35, s34, 31
	s_lshl_b64 s[16:17], s[34:35], 21
	s_add_u32 s42, s20, s16
	s_addc_u32 s43, s22, s17
	s_and_b64 s[16:17], s[40:41], exec
	s_cselect_b32 s35, s43, s13
	s_cselect_b32 s53, s42, s12
	s_add_u32 s54, s12, 0x10000
	s_addc_u32 s55, s13, 0
	s_add_u32 s44, s44, 0x100080
	v_mov_b32_e32 v2, 0
	s_addc_u32 s45, s45, 0
	s_mov_b32 s56, -2
	v_mov_b32_e32 v3, v2
	v_mov_b64_e32 v[4:5], 0
	v_mov_b64_e32 v[6:7], 0
	v_mov_b64_e32 v[8:9], 0
	v_mov_b64_e32 v[10:11], 0
	v_mov_b64_e32 v[12:13], 0
	v_mov_b64_e32 v[18:19], 0
	v_mov_b64_e32 v[20:21], 0
	v_mov_b64_e32 v[26:27], 0
	v_mov_b64_e32 v[28:29], 0
	v_mov_b64_e32 v[34:35], 0
	v_mov_b64_e32 v[36:37], 0
	v_mov_b64_e32 v[42:43], 0
	v_mov_b64_e32 v[44:45], 0
	v_mov_b64_e32 v[50:51], 0
	v_mov_b64_e32 v[52:53], 0
	v_mov_b64_e32 v[14:15], 0
	v_mov_b64_e32 v[16:17], 0
	v_mov_b64_e32 v[22:23], 0
	v_mov_b64_e32 v[24:25], 0
	v_mov_b64_e32 v[30:31], 0
	v_mov_b64_e32 v[32:33], 0
	v_mov_b64_e32 v[38:39], 0
	v_mov_b64_e32 v[40:41], 0
	v_mov_b64_e32 v[46:47], 0
	v_mov_b64_e32 v[48:49], 0
	v_mov_b64_e32 v[54:55], 0
	v_mov_b64_e32 v[56:57], 0
	v_mov_b64_e32 v[58:59], 0
	v_mov_b64_e32 v[60:61], 0
	v_mov_b64_e32 v[62:63], 0
	v_mov_b64_e32 v[64:65], 0
	v_mov_b64_e32 v[66:67], 0
	v_mov_b64_e32 v[68:69], 0
	v_mov_b64_e32 v[70:71], 0
	v_mov_b64_e32 v[72:73], 0
	v_mov_b64_e32 v[74:75], 0
	v_mov_b64_e32 v[76:77], 0
	v_mov_b64_e32 v[82:83], 0
	v_mov_b64_e32 v[84:85], 0
	v_mov_b64_e32 v[90:91], 0
	v_mov_b64_e32 v[92:93], 0
	v_mov_b64_e32 v[98:99], 0
	v_mov_b64_e32 v[100:101], 0
	v_mov_b64_e32 v[106:107], 0
	v_mov_b64_e32 v[108:109], 0
	v_mov_b64_e32 v[116:117], 0
	v_mov_b64_e32 v[118:119], 0
	v_mov_b64_e32 v[78:79], 0
	v_mov_b64_e32 v[80:81], 0
	v_mov_b64_e32 v[86:87], 0
	v_mov_b64_e32 v[88:89], 0
	v_mov_b64_e32 v[94:95], 0
	v_mov_b64_e32 v[96:97], 0
	v_mov_b64_e32 v[102:103], 0
	v_mov_b64_e32 v[104:105], 0
	v_mov_b64_e32 v[110:111], 0
	v_mov_b64_e32 v[112:113], 0
	v_mov_b64_e32 v[120:121], 0
	v_mov_b64_e32 v[122:123], 0
	v_mov_b64_e32 v[124:125], 0
	v_mov_b64_e32 v[126:127], 0
	v_mov_b64_e32 v[128:129], 0
	v_mov_b64_e32 v[130:131], 0

; template <class Epi, class Sched, bool ALIGN_EPI = false, bool SP2 = false, bool TILED_A = false, bool TILED_B = false, bool I8 = false>
; __device__ __forceinline__ void gemm_phase(PG8_LAS unsigned char* lds, const Gemm g, const Sched& S, const Epi& E) {
;     ...
;     for (;;) {
;         const bool has_next = S.next(ui + 1, nxt);
;         const char* nA = has_next ? (const char*)g.A + (size_t)nxt.pm * tstep : cA; const char* nB = has_next ? (const char*)g.Bt + (size_t)nxt.pn * tstep : cB;
;     ...
; #pragma unroll
;         for (int a = 0; a < 2; ++a)
; #pragma unroll
;             for (int b = 0; b < 2; ++b)
; #pragma unroll
;                 for (int m = 0; m < 4; ++m)
; #pragma unroll
;                     for (int n = 0; n < 2; ++n) acc[a][b][m][n] = MT<I8>::zero();
.LBB0_717:
	s_ashr_i32 s55, s54, 31
	s_lshl_b64 s[12:13], s[54:55], 20
	s_add_u32 s56, s20, s12
	s_addc_u32 s57, s25, s13
	s_and_b64 s[12:13], s[44:45], exec
	s_cselect_b32 s3, s57, s11
	s_cselect_b32 s9, s56, s10
	s_ashr_i32 s53, s52, 31
	s_lshl_b64 s[12:13], s[52:53], 20
	s_add_u32 s58, s26, s12
	s_addc_u32 s59, s27, s13
	s_and_b64 s[12:13], s[44:45], exec
	s_cselect_b32 s22, s59, s7
	s_cselect_b32 s23, s58, s6
	s_add_u32 s24, s6, 0x10000
	s_addc_u32 s48, s7, 0
	s_add_u32 s6, s10, 0x80080
	v_mov_b32_e32 v2, 0
	s_addc_u32 s7, s11, 0
	s_mov_b32 s53, -2
	s_waitcnt lgkmcnt(0)
	v_mov_b32_e32 v3, v2
	v_mov_b64_e32 v[4:5], 0
	v_mov_b64_e32 v[6:7], 0
	v_mov_b64_e32 v[8:9], 0
	v_mov_b64_e32 v[18:19], 0
	v_mov_b64_e32 v[20:21], 0
	v_mov_b64_e32 v[22:23], 0
	v_mov_b64_e32 v[24:25], 0
	v_mov_b64_e32 v[34:35], 0
	v_mov_b64_e32 v[36:37], 0
	v_mov_b64_e32 v[38:39], 0
	v_mov_b64_e32 v[40:41], 0
	v_mov_b64_e32 v[50:51], 0
	v_mov_b64_e32 v[52:53], 0
	v_mov_b64_e32 v[54:55], 0
	v_mov_b64_e32 v[56:57], 0
	v_mov_b64_e32 v[10:11], 0
	v_mov_b64_e32 v[12:13], 0
	v_mov_b64_e32 v[14:15], 0
	v_mov_b64_e32 v[16:17], 0
	v_mov_b64_e32 v[26:27], 0
	v_mov_b64_e32 v[28:29], 0
	v_mov_b64_e32 v[30:31], 0
	v_mov_b64_e32 v[32:33], 0
	v_mov_b64_e32 v[42:43], 0
	v_mov_b64_e32 v[44:45], 0
	v_mov_b64_e32 v[46:47], 0
	v_mov_b64_e32 v[48:49], 0
	v_mov_b64_e32 v[58:59], 0
	v_mov_b64_e32 v[60:61], 0
	v_mov_b64_e32 v[62:63], 0
	v_mov_b64_e32 v[64:65], 0
	v_mov_b64_e32 v[66:67], 0
	v_mov_b64_e32 v[68:69], 0
	v_mov_b64_e32 v[70:71], 0
	v_mov_b64_e32 v[72:73], 0
	v_mov_b64_e32 v[82:83], 0
	v_mov_b64_e32 v[84:85], 0
	v_mov_b64_e32 v[86:87], 0
	v_mov_b64_e32 v[88:89], 0
	v_mov_b64_e32 v[98:99], 0
	v_mov_b64_e32 v[100:101], 0
	v_mov_b64_e32 v[102:103], 0
	v_mov_b64_e32 v[104:105], 0
	v_mov_b64_e32 v[116:117], 0
	v_mov_b64_e32 v[118:119], 0
	v_mov_b64_e32 v[120:121], 0
	v_mov_b64_e32 v[122:123], 0
	v_mov_b64_e32 v[74:75], 0
	v_mov_b64_e32 v[76:77], 0
	v_mov_b64_e32 v[78:79], 0
	v_mov_b64_e32 v[80:81], 0
	v_mov_b64_e32 v[90:91], 0
	v_mov_b64_e32 v[92:93], 0
	v_mov_b64_e32 v[94:95], 0
	v_mov_b64_e32 v[96:97], 0
	v_mov_b64_e32 v[106:107], 0
	v_mov_b64_e32 v[108:109], 0
	v_mov_b64_e32 v[110:111], 0
	v_mov_b64_e32 v[112:113], 0
	v_mov_b64_e32 v[124:125], 0
	v_mov_b64_e32 v[126:127], 0
	v_mov_b64_e32 v[128:129], 0
	v_mov_b64_e32 v[130:131], 0

; template <class Epi, class Sched, bool ALIGN_EPI = false, bool SP2 = false, bool TILED_A = false, bool TILED_B = false, bool I8 = false>
; __device__ __forceinline__ void gemm_phase(PG8_LAS unsigned char* lds, const Gemm g, const Sched& S, const Epi& E) {
;     ...
;     for (;;) {
;         const bool has_next = S.next(ui + 1, nxt);
;         const char* nA = has_next ? (const char*)g.A + (size_t)nxt.pm * tstep : cA; const char* nB = has_next ? (const char*)g.Bt + (size_t)nxt.pn * tstep : cB;
;     ...
; #pragma unroll
;         for (int a = 0; a < 2; ++a)
; #pragma unroll
;             for (int b = 0; b < 2; ++b)
; #pragma unroll
;                 for (int m = 0; m < 4; ++m)
; #pragma unroll
;                     for (int n = 0; n < 2; ++n) acc[a][b][m][n] = MT<I8>::zero();
.LBB0_869:
	s_ashr_i32 s57, s56, 31
	s_lshl_b64 s[12:13], s[56:57], 22
	s_add_u32 s58, s28, s12
	s_addc_u32 s59, s29, s13
	s_and_b64 s[12:13], s[42:43], exec
	s_cselect_b32 s3, s59, s9
	s_cselect_b32 s7, s58, s8
	s_ashr_i32 s55, s54, 31
	s_lshl_b64 s[12:13], s[54:55], 22
	s_add_u32 s60, s25, s12
	s_addc_u32 s61, s26, s13
	s_and_b64 s[12:13], s[42:43], exec
	s_cselect_b32 s22, s61, s11
	s_cselect_b32 s23, s60, s10
	s_add_u32 s8, s8, 0xc000
	s_addc_u32 s9, s9, 0
	s_add_u32 s24, s10, 0x10000
	v_mov_b32_e32 v2, 0
	s_addc_u32 s55, s11, 0
	s_mov_b32 s57, -2
	v_mov_b32_e32 v3, v2
	v_mov_b64_e32 v[4:5], 0
	v_mov_b64_e32 v[6:7], 0
	v_mov_b64_e32 v[8:9], 0
	v_mov_b64_e32 v[10:11], 0
	v_mov_b64_e32 v[12:13], 0
	v_mov_b64_e32 v[14:15], 0
	v_mov_b64_e32 v[16:17], 0
	v_mov_b64_e32 v[18:19], 0
	v_mov_b64_e32 v[20:21], 0
	v_mov_b64_e32 v[22:23], 0
	v_mov_b64_e32 v[24:25], 0
	v_mov_b64_e32 v[26:27], 0
	v_mov_b64_e32 v[28:29], 0
	v_mov_b64_e32 v[30:31], 0
	v_mov_b64_e32 v[32:33], 0
	v_mov_b64_e32 v[66:67], 0
	v_mov_b64_e32 v[68:69], 0
	v_mov_b64_e32 v[70:71], 0
	v_mov_b64_e32 v[72:73], 0
	v_mov_b64_e32 v[74:75], 0
	v_mov_b64_e32 v[76:77], 0
	v_mov_b64_e32 v[78:79], 0
	v_mov_b64_e32 v[80:81], 0
	v_mov_b64_e32 v[82:83], 0
	v_mov_b64_e32 v[84:85], 0
	v_mov_b64_e32 v[86:87], 0
	v_mov_b64_e32 v[88:89], 0
	v_mov_b64_e32 v[90:91], 0
	v_mov_b64_e32 v[92:93], 0
	v_mov_b64_e32 v[94:95], 0
	v_mov_b64_e32 v[96:97], 0
	v_mov_b64_e32 v[34:35], 0
	v_mov_b64_e32 v[36:37], 0
	v_mov_b64_e32 v[38:39], 0
	v_mov_b64_e32 v[40:41], 0
	v_mov_b64_e32 v[42:43], 0
	v_mov_b64_e32 v[44:45], 0
	v_mov_b64_e32 v[46:47], 0
	v_mov_b64_e32 v[48:49], 0
	v_mov_b64_e32 v[50:51], 0
	v_mov_b64_e32 v[52:53], 0
	v_mov_b64_e32 v[54:55], 0
	v_mov_b64_e32 v[56:57], 0
	v_mov_b64_e32 v[58:59], 0
	v_mov_b64_e32 v[60:61], 0
	v_mov_b64_e32 v[62:63], 0
	v_mov_b64_e32 v[64:65], 0
	v_mov_b64_e32 v[98:99], 0
	v_mov_b64_e32 v[100:101], 0
	v_mov_b64_e32 v[102:103], 0
	v_mov_b64_e32 v[104:105], 0
	v_mov_b64_e32 v[106:107], 0
	v_mov_b64_e32 v[108:109], 0
	v_mov_b64_e32 v[110:111], 0
	v_mov_b64_e32 v[112:113], 0
	v_mov_b64_e32 v[116:117], 0
	v_mov_b64_e32 v[118:119], 0
	v_mov_b64_e32 v[120:121], 0
	v_mov_b64_e32 v[122:123], 0
	v_mov_b64_e32 v[124:125], 0
	v_mov_b64_e32 v[126:127], 0
	v_mov_b64_e32 v[128:129], 0
	v_mov_b64_e32 v[130:131], 0
